# MFMA order: chain (k0,k1 back-to-back per accumulator) + row snake so every transition between chains shares one operand fragment; second 16-group walks back
# speedup vs baseline: 1.0209x; 1.0084x over previous
.LBB0_127:
	s_add_u32 s12, s52, 0xfff00080
	s_addc_u32 s13, s53, -1
	s_add_i32 s57, 0, 0x10000
	s_cmp_eq_u32 s56, 60
	s_cselect_b32 s15, s18, s13
	s_cselect_b32 s14, s19, s12
	v_add_u32_e32 v142, s57, v143
	s_cselect_b32 s13, s45, s55
	s_cselect_b32 s12, s47, s54
	s_add_i32 s60, 0, 0x14000
	ds_read_b128 v[146:149], v142
	ds_read_b128 v[152:155], v142 offset:1024
	ds_read_b128 v[156:159], v142 offset:2048
	ds_read_b128 v[160:163], v142 offset:3072
	v_add_u32_e32 v142, s60, v143
	ds_read_b128 v[164:167], v142
	ds_read_b128 v[168:171], v142 offset:1024
	ds_read_b128 v[172:175], v142 offset:2048
	ds_read_b128 v[176:179], v142 offset:3072
	v_lshl_add_u64 v[192:193], s[52:53], 0, v[138:139]
	s_add_i32 m0, s27, 0xc000
	ds_read_b128 v[180:183], v151
	ds_read_b128 v[184:187], v151 offset:1024
	ds_read_b128 v[188:191], v151 offset:2048
	ds_read_b128 v[206:209], v151 offset:3072
	ds_read_b128 v[210:213], v151 offset:4096
	ds_read_b128 v[240:243], v151 offset:5120
	ds_read_b128 v[244:247], v151 offset:6144
	ds_read_b128 v[248:251], v151 offset:7168
	global_load_lds_dwordx4 v[192:193], off
	v_lshl_add_u64 v[192:193], s[52:53], 0, v[140:141]
	s_add_i32 m0, s27, 0xe000
	s_nop 0
	global_load_lds_dwordx4 v[192:193], off
	s_waitcnt vmcnt(8)
	s_waitcnt lgkmcnt(0)
	s_barrier
	s_waitcnt lgkmcnt(0)
	v_mfma_f32_16x16x32_bf16 v[128:131], v[146:149], v[180:183], v[128:131]
	v_mfma_f32_16x16x32_bf16 v[128:131], v[152:155], v[184:187], v[128:131]
	v_mfma_f32_16x16x32_bf16 v[124:127], v[160:163], v[184:187], v[124:127]
	v_mfma_f32_16x16x32_bf16 v[124:127], v[156:159], v[180:183], v[124:127]
	v_mfma_f32_16x16x32_bf16 v[108:111], v[156:159], v[188:191], v[108:111]
	v_mfma_f32_16x16x32_bf16 v[108:111], v[160:163], v[206:209], v[108:111]
	v_mfma_f32_16x16x32_bf16 v[112:115], v[152:155], v[206:209], v[112:115]
	v_mfma_f32_16x16x32_bf16 v[112:115], v[146:149], v[188:191], v[112:115]
	v_mfma_f32_16x16x32_bf16 v[96:99], v[146:149], v[210:213], v[96:99]
	v_mfma_f32_16x16x32_bf16 v[96:99], v[152:155], v[240:243], v[96:99]
	v_mfma_f32_16x16x32_bf16 v[92:95], v[160:163], v[240:243], v[92:95]
	v_mfma_f32_16x16x32_bf16 v[92:95], v[156:159], v[210:213], v[92:95]
	v_mfma_f32_16x16x32_bf16 v[76:79], v[156:159], v[244:247], v[76:79]
	v_mfma_f32_16x16x32_bf16 v[76:79], v[160:163], v[248:251], v[76:79]
	v_mfma_f32_16x16x32_bf16 v[80:83], v[152:155], v[248:251], v[80:83]
	v_mfma_f32_16x16x32_bf16 v[80:83], v[146:149], v[244:247], v[80:83]
	v_mfma_f32_16x16x32_bf16 v[72:75], v[164:167], v[244:247], v[72:75]
	v_mfma_f32_16x16x32_bf16 v[72:75], v[168:171], v[248:251], v[72:75]
	v_mfma_f32_16x16x32_bf16 v[68:71], v[176:179], v[248:251], v[68:71]
	v_mfma_f32_16x16x32_bf16 v[68:71], v[172:175], v[244:247], v[68:71]
	v_mfma_f32_16x16x32_bf16 v[84:87], v[172:175], v[210:213], v[84:87]
	v_mfma_f32_16x16x32_bf16 v[84:87], v[176:179], v[240:243], v[84:87]
	v_mfma_f32_16x16x32_bf16 v[88:91], v[168:171], v[240:243], v[88:91]
	v_mfma_f32_16x16x32_bf16 v[88:91], v[164:167], v[210:213], v[88:91]
	v_mfma_f32_16x16x32_bf16 v[104:107], v[164:167], v[188:191], v[104:107]
	v_mfma_f32_16x16x32_bf16 v[104:107], v[168:171], v[206:209], v[104:107]
	v_mfma_f32_16x16x32_bf16 v[100:103], v[176:179], v[206:209], v[100:103]
	v_mfma_f32_16x16x32_bf16 v[100:103], v[172:175], v[188:191], v[100:103]
	v_mfma_f32_16x16x32_bf16 v[116:119], v[172:175], v[180:183], v[116:119]
	v_mfma_f32_16x16x32_bf16 v[116:119], v[176:179], v[184:187], v[116:119]
	v_mfma_f32_16x16x32_bf16 v[120:123], v[168:171], v[184:187], v[120:123]
	v_mfma_f32_16x16x32_bf16 v[120:123], v[164:167], v[180:183], v[120:123]
	s_barrier
	s_add_i32 s57, s57, s26
	v_lshl_add_u64 v[192:193], s[12:13], 0, v[2:3]
	s_mov_b32 m0, s57
	ds_read_b128 v[180:183], v151 offset:16384
	ds_read_b128 v[184:187], v151 offset:17408
	ds_read_b128 v[188:191], v151 offset:18432
	ds_read_b128 v[206:209], v151 offset:19456
	ds_read_b128 v[210:213], v151 offset:20480
	ds_read_b128 v[240:243], v151 offset:21504
	ds_read_b128 v[244:247], v151 offset:22528
	ds_read_b128 v[248:251], v151 offset:23552
	global_load_lds_dwordx4 v[192:193], off
	s_add_i32 m0, s57, 0x2000
	s_add_u32 s58, s12, 0x100000
	v_lshl_add_u64 v[214:215], s[12:13], 0, v[132:133]
	s_addc_u32 s59, s13, 0
	s_add_i32 s57, s60, s26
	global_load_lds_dwordx4 v[214:215], off
	v_lshl_add_u64 v[224:225], s[58:59], 0, v[2:3]
	s_mov_b32 m0, s57
	v_lshl_add_u64 v[226:227], s[14:15], 0, v[134:135]
	global_load_lds_dwordx4 v[224:225], off
	v_lshl_add_u64 v[224:225], s[58:59], 0, v[132:133]
	s_add_i32 m0, s57, 0x2000
	s_nop 0
	global_load_lds_dwordx4 v[224:225], off
	v_lshl_add_u64 v[224:225], s[14:15], 0, v[136:137]
	s_mov_b32 m0, s27
	s_nop 0
	global_load_lds_dwordx4 v[224:225], off
	s_mov_b32 m0, s28
	s_nop 0
	global_load_lds_dwordx4 v[226:227], off
	s_waitcnt vmcnt(8)
	s_waitcnt lgkmcnt(0)
	s_barrier
	s_waitcnt lgkmcnt(0)
	v_mfma_f32_16x16x32_bf16 v[64:67], v[146:149], v[180:183], v[64:67]
	v_mfma_f32_16x16x32_bf16 v[64:67], v[152:155], v[184:187], v[64:67]
	v_mfma_f32_16x16x32_bf16 v[60:63], v[160:163], v[184:187], v[60:63]
	v_mfma_f32_16x16x32_bf16 v[60:63], v[156:159], v[180:183], v[60:63]
	v_mfma_f32_16x16x32_bf16 v[44:47], v[156:159], v[188:191], v[44:47]
	v_mfma_f32_16x16x32_bf16 v[44:47], v[160:163], v[206:209], v[44:47]
	v_mfma_f32_16x16x32_bf16 v[52:55], v[152:155], v[206:209], v[52:55]
	v_mfma_f32_16x16x32_bf16 v[52:55], v[146:149], v[188:191], v[52:55]
	v_mfma_f32_16x16x32_bf16 v[36:39], v[146:149], v[210:213], v[36:39]
	v_mfma_f32_16x16x32_bf16 v[36:39], v[152:155], v[240:243], v[36:39]
	v_mfma_f32_16x16x32_bf16 v[28:31], v[160:163], v[240:243], v[28:31]
	v_mfma_f32_16x16x32_bf16 v[28:31], v[156:159], v[210:213], v[28:31]
	v_mfma_f32_16x16x32_bf16 v[12:15], v[156:159], v[244:247], v[12:15]
	v_mfma_f32_16x16x32_bf16 v[12:15], v[160:163], v[248:251], v[12:15]
	v_mfma_f32_16x16x32_bf16 v[20:23], v[152:155], v[248:251], v[20:23]
	v_mfma_f32_16x16x32_bf16 v[20:23], v[146:149], v[244:247], v[20:23]
	v_mfma_f32_16x16x32_bf16 v[8:11], v[164:167], v[244:247], v[8:11]
	v_mfma_f32_16x16x32_bf16 v[8:11], v[168:171], v[248:251], v[8:11]
	v_mfma_f32_16x16x32_bf16 v[4:7], v[176:179], v[248:251], v[4:7]
	v_mfma_f32_16x16x32_bf16 v[4:7], v[172:175], v[244:247], v[4:7]
	v_mfma_f32_16x16x32_bf16 v[16:19], v[172:175], v[210:213], v[16:19]
	v_mfma_f32_16x16x32_bf16 v[16:19], v[176:179], v[240:243], v[16:19]
	v_mfma_f32_16x16x32_bf16 v[24:27], v[168:171], v[240:243], v[24:27]
	v_mfma_f32_16x16x32_bf16 v[24:27], v[164:167], v[210:213], v[24:27]
	v_mfma_f32_16x16x32_bf16 v[40:43], v[164:167], v[188:191], v[40:43]
	v_mfma_f32_16x16x32_bf16 v[40:43], v[168:171], v[206:209], v[40:43]
	v_mfma_f32_16x16x32_bf16 v[32:35], v[176:179], v[206:209], v[32:35]
	v_mfma_f32_16x16x32_bf16 v[32:35], v[172:175], v[188:191], v[32:35]
	v_mfma_f32_16x16x32_bf16 v[48:51], v[172:175], v[180:183], v[48:51]
	v_mfma_f32_16x16x32_bf16 v[48:51], v[176:179], v[184:187], v[48:51]
	v_mfma_f32_16x16x32_bf16 v[56:59], v[168:171], v[184:187], v[56:59]
	v_mfma_f32_16x16x32_bf16 v[56:59], v[164:167], v[180:183], v[56:59]
	s_barrier
	s_add_i32 s57, 0, 0x18000
	v_add_u32_e32 v142, s57, v143
	s_add_i32 s58, 0, 0x1c000
	ds_read_b128 v[146:149], v142
	ds_read_b128 v[152:155], v142 offset:1024
	ds_read_b128 v[156:159], v142 offset:2048
	ds_read_b128 v[160:163], v142 offset:3072
	v_add_u32_e32 v142, s58, v143
	ds_read_b128 v[164:167], v142
	ds_read_b128 v[168:171], v142 offset:1024
	ds_read_b128 v[172:175], v142 offset:2048
	ds_read_b128 v[176:179], v142 offset:3072
	s_add_u32 s14, s14, 0x100000
	s_addc_u32 s15, s15, 0
	s_mov_b32 m0, s29
	v_lshl_add_u64 v[228:229], s[14:15], 0, v[136:137]
	ds_read_b128 v[180:183], v151 offset:32768
	ds_read_b128 v[184:187], v151 offset:33792
	ds_read_b128 v[188:191], v151 offset:34816
	ds_read_b128 v[206:209], v151 offset:35840
	ds_read_b128 v[210:213], v151 offset:36864
	ds_read_b128 v[240:243], v151 offset:37888
	ds_read_b128 v[244:247], v151 offset:38912
	ds_read_b128 v[248:251], v151 offset:39936
	global_load_lds_dwordx4 v[228:229], off
	v_lshl_add_u64 v[228:229], s[14:15], 0, v[134:135]
	s_mov_b32 m0, s30
	s_nop 0
	global_load_lds_dwordx4 v[228:229], off
	s_waitcnt vmcnt(8)
	s_waitcnt lgkmcnt(0)
	s_barrier
	s_waitcnt lgkmcnt(0)
	v_mfma_f32_16x16x32_bf16 v[128:131], v[146:149], v[180:183], v[128:131]
	v_mfma_f32_16x16x32_bf16 v[128:131], v[152:155], v[184:187], v[128:131]
	v_mfma_f32_16x16x32_bf16 v[124:127], v[160:163], v[184:187], v[124:127]
	v_mfma_f32_16x16x32_bf16 v[124:127], v[156:159], v[180:183], v[124:127]
	v_mfma_f32_16x16x32_bf16 v[108:111], v[156:159], v[188:191], v[108:111]
	v_mfma_f32_16x16x32_bf16 v[108:111], v[160:163], v[206:209], v[108:111]
	v_mfma_f32_16x16x32_bf16 v[112:115], v[152:155], v[206:209], v[112:115]
	v_mfma_f32_16x16x32_bf16 v[112:115], v[146:149], v[188:191], v[112:115]
	v_mfma_f32_16x16x32_bf16 v[96:99], v[146:149], v[210:213], v[96:99]
	v_mfma_f32_16x16x32_bf16 v[96:99], v[152:155], v[240:243], v[96:99]
	v_mfma_f32_16x16x32_bf16 v[92:95], v[160:163], v[240:243], v[92:95]
	v_mfma_f32_16x16x32_bf16 v[92:95], v[156:159], v[210:213], v[92:95]
	v_mfma_f32_16x16x32_bf16 v[76:79], v[156:159], v[244:247], v[76:79]
	v_mfma_f32_16x16x32_bf16 v[76:79], v[160:163], v[248:251], v[76:79]
	v_mfma_f32_16x16x32_bf16 v[80:83], v[152:155], v[248:251], v[80:83]
	v_mfma_f32_16x16x32_bf16 v[80:83], v[146:149], v[244:247], v[80:83]
	v_mfma_f32_16x16x32_bf16 v[72:75], v[164:167], v[244:247], v[72:75]
	v_mfma_f32_16x16x32_bf16 v[72:75], v[168:171], v[248:251], v[72:75]
	v_mfma_f32_16x16x32_bf16 v[68:71], v[176:179], v[248:251], v[68:71]
	v_mfma_f32_16x16x32_bf16 v[68:71], v[172:175], v[244:247], v[68:71]
	v_mfma_f32_16x16x32_bf16 v[84:87], v[172:175], v[210:213], v[84:87]
	v_mfma_f32_16x16x32_bf16 v[84:87], v[176:179], v[240:243], v[84:87]
	v_mfma_f32_16x16x32_bf16 v[88:91], v[168:171], v[240:243], v[88:91]
	v_mfma_f32_16x16x32_bf16 v[88:91], v[164:167], v[210:213], v[88:91]
	v_mfma_f32_16x16x32_bf16 v[104:107], v[164:167], v[188:191], v[104:107]
	v_mfma_f32_16x16x32_bf16 v[104:107], v[168:171], v[206:209], v[104:107]
	v_mfma_f32_16x16x32_bf16 v[100:103], v[176:179], v[206:209], v[100:103]
	v_mfma_f32_16x16x32_bf16 v[100:103], v[172:175], v[188:191], v[100:103]
	v_mfma_f32_16x16x32_bf16 v[116:119], v[172:175], v[180:183], v[116:119]
	v_mfma_f32_16x16x32_bf16 v[116:119], v[176:179], v[184:187], v[116:119]
	v_mfma_f32_16x16x32_bf16 v[120:123], v[168:171], v[184:187], v[120:123]
	v_mfma_f32_16x16x32_bf16 v[120:123], v[164:167], v[180:183], v[120:123]
	s_barrier
	s_add_i32 s14, s57, s26
	v_lshl_add_u64 v[192:193], v[192:193], 0, s[4:5]
	s_mov_b32 m0, s14
	ds_read_b128 v[180:183], v151 offset:49152
	ds_read_b128 v[184:187], v151 offset:50176
	ds_read_b128 v[188:191], v151 offset:51200
	ds_read_b128 v[206:209], v151 offset:52224
	ds_read_b128 v[210:213], v151 offset:53248
	ds_read_b128 v[240:243], v151 offset:54272
	ds_read_b128 v[244:247], v151 offset:55296
	ds_read_b128 v[248:251], v151 offset:56320
	global_load_lds_dwordx4 v[192:193], off
	s_add_i32 m0, s14, 0x2000
	s_add_u32 s12, s12, 0x100080
	v_lshl_add_u64 v[192:193], v[214:215], 0, s[4:5]
	s_addc_u32 s13, s13, 0
	s_add_i32 s14, s58, s26
	global_load_lds_dwordx4 v[192:193], off
	v_lshl_add_u64 v[192:193], s[12:13], 0, v[2:3]
	s_mov_b32 m0, s14
	s_nop 0
	global_load_lds_dwordx4 v[192:193], off
	v_lshl_add_u64 v[192:193], s[12:13], 0, v[132:133]
	s_add_i32 m0, s14, 0x2000
	s_nop 0
	global_load_lds_dwordx4 v[192:193], off
	v_lshl_add_u64 v[192:193], v[224:225], 0, s[4:5]
	s_mov_b32 m0, s31
	s_nop 0
	global_load_lds_dwordx4 v[192:193], off
	v_lshl_add_u64 v[192:193], v[226:227], 0, s[4:5]
	s_mov_b32 m0, s34
	s_nop 0
	global_load_lds_dwordx4 v[192:193], off
	s_waitcnt vmcnt(8)
	s_waitcnt lgkmcnt(0)
	s_barrier
	s_waitcnt lgkmcnt(0)
	v_mfma_f32_16x16x32_bf16 v[64:67], v[146:149], v[180:183], v[64:67]
	v_mfma_f32_16x16x32_bf16 v[64:67], v[152:155], v[184:187], v[64:67]
	v_mfma_f32_16x16x32_bf16 v[60:63], v[160:163], v[184:187], v[60:63]
	v_mfma_f32_16x16x32_bf16 v[60:63], v[156:159], v[180:183], v[60:63]
	v_mfma_f32_16x16x32_bf16 v[44:47], v[156:159], v[188:191], v[44:47]
	v_mfma_f32_16x16x32_bf16 v[44:47], v[160:163], v[206:209], v[44:47]
	v_mfma_f32_16x16x32_bf16 v[52:55], v[152:155], v[206:209], v[52:55]
	v_mfma_f32_16x16x32_bf16 v[52:55], v[146:149], v[188:191], v[52:55]
	v_mfma_f32_16x16x32_bf16 v[36:39], v[146:149], v[210:213], v[36:39]
	v_mfma_f32_16x16x32_bf16 v[36:39], v[152:155], v[240:243], v[36:39]
	v_mfma_f32_16x16x32_bf16 v[28:31], v[160:163], v[240:243], v[28:31]
	v_mfma_f32_16x16x32_bf16 v[28:31], v[156:159], v[210:213], v[28:31]
	v_mfma_f32_16x16x32_bf16 v[12:15], v[156:159], v[244:247], v[12:15]
	v_mfma_f32_16x16x32_bf16 v[12:15], v[160:163], v[248:251], v[12:15]
	v_mfma_f32_16x16x32_bf16 v[20:23], v[152:155], v[248:251], v[20:23]
	v_mfma_f32_16x16x32_bf16 v[20:23], v[146:149], v[244:247], v[20:23]
	v_mfma_f32_16x16x32_bf16 v[8:11], v[164:167], v[244:247], v[8:11]
	v_mfma_f32_16x16x32_bf16 v[8:11], v[168:171], v[248:251], v[8:11]
	v_mfma_f32_16x16x32_bf16 v[4:7], v[176:179], v[248:251], v[4:7]
	v_mfma_f32_16x16x32_bf16 v[4:7], v[172:175], v[244:247], v[4:7]
	v_mfma_f32_16x16x32_bf16 v[16:19], v[172:175], v[210:213], v[16:19]
	v_mfma_f32_16x16x32_bf16 v[16:19], v[176:179], v[240:243], v[16:19]
	v_mfma_f32_16x16x32_bf16 v[24:27], v[168:171], v[240:243], v[24:27]
	v_mfma_f32_16x16x32_bf16 v[24:27], v[164:167], v[210:213], v[24:27]
	v_mfma_f32_16x16x32_bf16 v[40:43], v[164:167], v[188:191], v[40:43]
	v_mfma_f32_16x16x32_bf16 v[40:43], v[168:171], v[206:209], v[40:43]
	v_mfma_f32_16x16x32_bf16 v[32:35], v[176:179], v[206:209], v[32:35]
	v_mfma_f32_16x16x32_bf16 v[32:35], v[172:175], v[188:191], v[32:35]
	v_mfma_f32_16x16x32_bf16 v[48:51], v[172:175], v[180:183], v[48:51]
	v_mfma_f32_16x16x32_bf16 v[48:51], v[176:179], v[184:187], v[48:51]
	v_mfma_f32_16x16x32_bf16 v[56:59], v[168:171], v[184:187], v[56:59]
	v_mfma_f32_16x16x32_bf16 v[56:59], v[164:167], v[180:183], v[56:59]
	s_barrier
	s_add_i32 s56, s56, 2
	s_add_u32 s52, s52, 0x100
	s_addc_u32 s53, s53, 0
	s_add_u32 s54, s54, 0x100
	s_addc_u32 s55, s55, 0
	s_cmp_gt_u32 s56, 61
	s_cbranch_scc0 .LBB0_127
	s_and_b64 vcc, exec, s[42:43]
	s_cbranch_vccz .LBB0_130
	s_barrier

.LBB0_1013:
	s_add_u32 s14, s60, 0x100
	s_addc_u32 s15, s61, 0
	s_add_i32 s70, 0, 0x10000
	s_cmp_eq_u32 s69, 60
	s_cselect_b32 s25, s3, s15
	s_cselect_b32 s24, s28, s14
	s_cselect_b32 s19, s29, s68
	s_cselect_b32 s18, s53, s55
	s_add_i32 s71, 0, 0x14000
	v_add_u32_e32 v64, s70, v178
	v_add_u32_e32 v160, s71, v178
	ds_read_b128 v[48:51], v64
	ds_read_b128 v[56:59], v64 offset:1024
	ds_read_b128 v[60:63], v64 offset:2048
	ds_read_b128 v[64:67], v64 offset:3072
	ds_read_b128 v[148:151], v160
	ds_read_b128 v[152:155], v160 offset:1024
	ds_read_b128 v[156:159], v160 offset:2048
	ds_read_b128 v[160:163], v160 offset:3072
	v_lshl_add_u64 v[214:215], s[60:61], 0, v[166:167]
	s_add_i32 m0, s36, 0xc000
	ds_read_b128 v[170:173], v180
	ds_read_b128 v[174:177], v180 offset:1024
	ds_read_b128 v[182:185], v180 offset:2048
	ds_read_b128 v[186:189], v180 offset:3072
	ds_read_b128 v[190:193], v180 offset:4096
	ds_read_b128 v[206:209], v180 offset:5120
	ds_read_b128 v[210:213], v180 offset:6144
	ds_read_b128 v[224:227], v180 offset:7168
	global_load_lds_dwordx4 v[214:215], off
	v_lshl_add_u64 v[214:215], s[60:61], 0, v[168:169]
	s_add_i32 m0, s36, 0xe000
	s_nop 0
	global_load_lds_dwordx4 v[214:215], off
	s_waitcnt vmcnt(8)
	s_waitcnt lgkmcnt(0)
	s_barrier
	s_waitcnt lgkmcnt(0)
	v_mfma_f32_16x16x32_bf16 v[144:147], v[48:51], v[170:173], v[144:147]
	v_mfma_f32_16x16x32_bf16 v[144:147], v[56:59], v[174:177], v[144:147]
	v_mfma_f32_16x16x32_bf16 v[140:143], v[64:67], v[174:177], v[140:143]
	v_mfma_f32_16x16x32_bf16 v[140:143], v[60:63], v[170:173], v[140:143]
	v_mfma_f32_16x16x32_bf16 v[124:127], v[60:63], v[182:185], v[124:127]
	v_mfma_f32_16x16x32_bf16 v[124:127], v[64:67], v[186:189], v[124:127]
	v_mfma_f32_16x16x32_bf16 v[128:131], v[56:59], v[186:189], v[128:131]
	v_mfma_f32_16x16x32_bf16 v[128:131], v[48:51], v[182:185], v[128:131]
	v_mfma_f32_16x16x32_bf16 v[112:115], v[48:51], v[190:193], v[112:115]
	v_mfma_f32_16x16x32_bf16 v[112:115], v[56:59], v[206:209], v[112:115]
	v_mfma_f32_16x16x32_bf16 v[108:111], v[64:67], v[206:209], v[108:111]
	v_mfma_f32_16x16x32_bf16 v[108:111], v[60:63], v[190:193], v[108:111]
	v_mfma_f32_16x16x32_bf16 v[92:95], v[60:63], v[210:213], v[92:95]
	v_mfma_f32_16x16x32_bf16 v[92:95], v[64:67], v[224:227], v[92:95]
	v_mfma_f32_16x16x32_bf16 v[96:99], v[56:59], v[224:227], v[96:99]
	v_mfma_f32_16x16x32_bf16 v[96:99], v[48:51], v[210:213], v[96:99]
	v_mfma_f32_16x16x32_bf16 v[88:91], v[148:151], v[210:213], v[88:91]
	v_mfma_f32_16x16x32_bf16 v[88:91], v[152:155], v[224:227], v[88:91]
	v_mfma_f32_16x16x32_bf16 v[84:87], v[160:163], v[224:227], v[84:87]
	v_mfma_f32_16x16x32_bf16 v[84:87], v[156:159], v[210:213], v[84:87]
	v_mfma_f32_16x16x32_bf16 v[100:103], v[156:159], v[190:193], v[100:103]
	v_mfma_f32_16x16x32_bf16 v[100:103], v[160:163], v[206:209], v[100:103]
	v_mfma_f32_16x16x32_bf16 v[104:107], v[152:155], v[206:209], v[104:107]
	v_mfma_f32_16x16x32_bf16 v[104:107], v[148:151], v[190:193], v[104:107]
	v_mfma_f32_16x16x32_bf16 v[120:123], v[148:151], v[182:185], v[120:123]
	v_mfma_f32_16x16x32_bf16 v[120:123], v[152:155], v[186:189], v[120:123]
	v_mfma_f32_16x16x32_bf16 v[116:119], v[160:163], v[186:189], v[116:119]
	v_mfma_f32_16x16x32_bf16 v[116:119], v[156:159], v[182:185], v[116:119]
	v_mfma_f32_16x16x32_bf16 v[132:135], v[156:159], v[170:173], v[132:135]
	v_mfma_f32_16x16x32_bf16 v[132:135], v[160:163], v[174:177], v[132:135]
	v_mfma_f32_16x16x32_bf16 v[136:139], v[152:155], v[174:177], v[136:139]
	v_mfma_f32_16x16x32_bf16 v[136:139], v[148:151], v[170:173], v[136:139]
	s_barrier
	s_add_i32 s60, s70, s35
	v_lshl_add_u64 v[214:215], s[18:19], 0, v[2:3]
	s_mov_b32 m0, s60
	ds_read_b128 v[170:173], v180 offset:16384
	ds_read_b128 v[174:177], v180 offset:17408
	ds_read_b128 v[182:185], v180 offset:18432
	ds_read_b128 v[186:189], v180 offset:19456
	ds_read_b128 v[190:193], v180 offset:20480
	ds_read_b128 v[206:209], v180 offset:21504
	ds_read_b128 v[210:213], v180 offset:22528
	ds_read_b128 v[224:227], v180 offset:23552
	global_load_lds_dwordx4 v[214:215], off
	s_add_i32 m0, s60, 0x2000
	s_add_u32 s60, s18, 0x100000
	v_lshl_add_u64 v[228:229], s[18:19], 0, v[164:165]
	s_addc_u32 s61, s19, 0
	s_add_i32 s70, s71, s35
	global_load_lds_dwordx4 v[228:229], off
	v_lshl_add_u64 v[230:231], s[60:61], 0, v[2:3]
	s_mov_b32 m0, s70
	v_lshl_add_u64 v[240:241], s[24:25], 0, v[164:165]
	global_load_lds_dwordx4 v[230:231], off
	v_lshl_add_u64 v[230:231], s[60:61], 0, v[164:165]
	s_add_i32 m0, s70, 0x2000
	s_nop 0
	global_load_lds_dwordx4 v[230:231], off
	v_lshl_add_u64 v[230:231], s[24:25], 0, v[2:3]
	s_mov_b32 m0, s36
	s_nop 0
	global_load_lds_dwordx4 v[230:231], off
	s_mov_b32 m0, s37
	s_nop 0
	global_load_lds_dwordx4 v[240:241], off
	s_waitcnt vmcnt(8)
	s_waitcnt lgkmcnt(0)
	s_barrier
	s_waitcnt lgkmcnt(0)
	v_mfma_f32_16x16x32_bf16 v[80:83], v[48:51], v[170:173], v[80:83]
	v_mfma_f32_16x16x32_bf16 v[80:83], v[56:59], v[174:177], v[80:83]
	v_mfma_f32_16x16x32_bf16 v[76:79], v[64:67], v[174:177], v[76:79]
	v_mfma_f32_16x16x32_bf16 v[76:79], v[60:63], v[170:173], v[76:79]
	v_mfma_f32_16x16x32_bf16 v[44:47], v[60:63], v[182:185], v[44:47]
	v_mfma_f32_16x16x32_bf16 v[44:47], v[64:67], v[186:189], v[44:47]
	v_mfma_f32_16x16x32_bf16 v[52:55], v[56:59], v[186:189], v[52:55]
	v_mfma_f32_16x16x32_bf16 v[52:55], v[48:51], v[182:185], v[52:55]
	v_mfma_f32_16x16x32_bf16 v[32:35], v[48:51], v[190:193], v[32:35]
	v_mfma_f32_16x16x32_bf16 v[32:35], v[56:59], v[206:209], v[32:35]
	v_mfma_f32_16x16x32_bf16 v[28:31], v[64:67], v[206:209], v[28:31]
	v_mfma_f32_16x16x32_bf16 v[28:31], v[60:63], v[190:193], v[28:31]
	v_mfma_f32_16x16x32_bf16 v[12:15], v[60:63], v[210:213], v[12:15]
	v_mfma_f32_16x16x32_bf16 v[12:15], v[64:67], v[224:227], v[12:15]
	v_mfma_f32_16x16x32_bf16 v[16:19], v[56:59], v[224:227], v[16:19]
	v_mfma_f32_16x16x32_bf16 v[16:19], v[48:51], v[210:213], v[16:19]
	v_mfma_f32_16x16x32_bf16 v[48:51], v[148:151], v[170:173], v[72:75]
	v_mfma_f32_16x16x32_bf16 v[48:51], v[152:155], v[174:177], v[48:51]
	v_mfma_f32_16x16x32_bf16 v[56:59], v[156:159], v[170:173], v[68:71]
	v_mfma_f32_16x16x32_bf16 v[56:59], v[160:163], v[174:177], v[56:59]
	v_mfma_f32_16x16x32_bf16 v[4:7], v[156:159], v[210:213], v[4:7]
	v_mfma_f32_16x16x32_bf16 v[4:7], v[160:163], v[224:227], v[4:7]
	v_mfma_f32_16x16x32_bf16 v[8:11], v[152:155], v[224:227], v[8:11]
	v_mfma_f32_16x16x32_bf16 v[8:11], v[148:151], v[210:213], v[8:11]
	v_mfma_f32_16x16x32_bf16 v[24:27], v[148:151], v[190:193], v[24:27]
	v_mfma_f32_16x16x32_bf16 v[24:27], v[152:155], v[206:209], v[24:27]
	v_mfma_f32_16x16x32_bf16 v[20:23], v[160:163], v[206:209], v[20:23]
	v_mfma_f32_16x16x32_bf16 v[20:23], v[156:159], v[190:193], v[20:23]
	v_mfma_f32_16x16x32_bf16 v[36:39], v[156:159], v[182:185], v[36:39]
	v_mfma_f32_16x16x32_bf16 v[36:39], v[160:163], v[186:189], v[36:39]
	v_mfma_f32_16x16x32_bf16 v[40:43], v[152:155], v[186:189], v[40:43]
	v_mfma_f32_16x16x32_bf16 v[40:43], v[148:151], v[182:185], v[40:43]
	s_barrier
	s_add_i32 s60, 0, 0x18000
	s_add_i32 s61, 0, 0x1c000
	v_add_u32_e32 v72, s60, v178
	v_add_u32_e32 v160, s61, v178
	ds_read_b128 v[60:63], v72
	ds_read_b128 v[64:67], v72 offset:1024
	ds_read_b128 v[68:71], v72 offset:2048
	ds_read_b128 v[72:75], v72 offset:3072
	ds_read_b128 v[148:151], v160
	ds_read_b128 v[152:155], v160 offset:1024
	ds_read_b128 v[156:159], v160 offset:2048
	ds_read_b128 v[160:163], v160 offset:3072
	s_add_u32 s24, s24, 0x100000
	s_addc_u32 s25, s25, 0
	s_mov_b32 m0, s62
	v_lshl_add_u64 v[242:243], s[24:25], 0, v[2:3]
	ds_read_b128 v[170:173], v180 offset:32768
	ds_read_b128 v[174:177], v180 offset:33792
	ds_read_b128 v[182:185], v180 offset:34816
	ds_read_b128 v[186:189], v180 offset:35840
	ds_read_b128 v[190:193], v180 offset:36864
	ds_read_b128 v[206:209], v180 offset:37888
	ds_read_b128 v[210:213], v180 offset:38912
	ds_read_b128 v[224:227], v180 offset:39936
	global_load_lds_dwordx4 v[242:243], off
	v_lshl_add_u64 v[242:243], s[24:25], 0, v[164:165]
	s_mov_b32 m0, s63
	s_nop 0
	global_load_lds_dwordx4 v[242:243], off
	s_waitcnt vmcnt(8)
	s_waitcnt lgkmcnt(0)
	s_barrier
	s_waitcnt lgkmcnt(0)
	v_mfma_f32_16x16x32_bf16 v[144:147], v[60:63], v[170:173], v[144:147]
	v_mfma_f32_16x16x32_bf16 v[144:147], v[64:67], v[174:177], v[144:147]
	v_mfma_f32_16x16x32_bf16 v[140:143], v[72:75], v[174:177], v[140:143]
	v_mfma_f32_16x16x32_bf16 v[140:143], v[68:71], v[170:173], v[140:143]
	v_mfma_f32_16x16x32_bf16 v[124:127], v[68:71], v[182:185], v[124:127]
	v_mfma_f32_16x16x32_bf16 v[124:127], v[72:75], v[186:189], v[124:127]
	v_mfma_f32_16x16x32_bf16 v[128:131], v[64:67], v[186:189], v[128:131]
	v_mfma_f32_16x16x32_bf16 v[128:131], v[60:63], v[182:185], v[128:131]
	v_mfma_f32_16x16x32_bf16 v[112:115], v[60:63], v[190:193], v[112:115]
	v_mfma_f32_16x16x32_bf16 v[112:115], v[64:67], v[206:209], v[112:115]
	v_mfma_f32_16x16x32_bf16 v[108:111], v[72:75], v[206:209], v[108:111]
	v_mfma_f32_16x16x32_bf16 v[108:111], v[68:71], v[190:193], v[108:111]
	v_mfma_f32_16x16x32_bf16 v[92:95], v[68:71], v[210:213], v[92:95]
	v_mfma_f32_16x16x32_bf16 v[92:95], v[72:75], v[224:227], v[92:95]
	v_mfma_f32_16x16x32_bf16 v[96:99], v[64:67], v[224:227], v[96:99]
	v_mfma_f32_16x16x32_bf16 v[96:99], v[60:63], v[210:213], v[96:99]
	v_mfma_f32_16x16x32_bf16 v[88:91], v[148:151], v[210:213], v[88:91]
	v_mfma_f32_16x16x32_bf16 v[88:91], v[152:155], v[224:227], v[88:91]
	v_mfma_f32_16x16x32_bf16 v[84:87], v[160:163], v[224:227], v[84:87]
	v_mfma_f32_16x16x32_bf16 v[84:87], v[156:159], v[210:213], v[84:87]
	v_mfma_f32_16x16x32_bf16 v[100:103], v[156:159], v[190:193], v[100:103]
	v_mfma_f32_16x16x32_bf16 v[100:103], v[160:163], v[206:209], v[100:103]
	v_mfma_f32_16x16x32_bf16 v[104:107], v[152:155], v[206:209], v[104:107]
	v_mfma_f32_16x16x32_bf16 v[104:107], v[148:151], v[190:193], v[104:107]
	v_mfma_f32_16x16x32_bf16 v[120:123], v[148:151], v[182:185], v[120:123]
	v_mfma_f32_16x16x32_bf16 v[120:123], v[152:155], v[186:189], v[120:123]
	v_mfma_f32_16x16x32_bf16 v[116:119], v[160:163], v[186:189], v[116:119]
	v_mfma_f32_16x16x32_bf16 v[116:119], v[156:159], v[182:185], v[116:119]
	v_mfma_f32_16x16x32_bf16 v[132:135], v[156:159], v[170:173], v[132:135]
	v_mfma_f32_16x16x32_bf16 v[132:135], v[160:163], v[174:177], v[132:135]
	v_mfma_f32_16x16x32_bf16 v[136:139], v[152:155], v[174:177], v[136:139]
	v_mfma_f32_16x16x32_bf16 v[136:139], v[148:151], v[170:173], v[136:139]
	s_barrier
	s_add_i32 s24, s60, s35
	v_lshl_add_u64 v[214:215], v[214:215], 0, s[4:5]
	s_mov_b32 m0, s24
	ds_read_b128 v[170:173], v180 offset:49152
	ds_read_b128 v[174:177], v180 offset:50176
	ds_read_b128 v[182:185], v180 offset:51200
	ds_read_b128 v[186:189], v180 offset:52224
	ds_read_b128 v[190:193], v180 offset:53248
	ds_read_b128 v[206:209], v180 offset:54272
	ds_read_b128 v[210:213], v180 offset:55296
	ds_read_b128 v[224:227], v180 offset:56320
	global_load_lds_dwordx4 v[214:215], off
	s_add_i32 m0, s24, 0x2000
	s_add_u32 s18, s18, 0x100080
	v_lshl_add_u64 v[214:215], v[228:229], 0, s[4:5]
	s_addc_u32 s19, s19, 0
	s_add_i32 s24, s61, s35
	global_load_lds_dwordx4 v[214:215], off
	v_lshl_add_u64 v[214:215], s[18:19], 0, v[2:3]
	s_mov_b32 m0, s24
	s_nop 0
	global_load_lds_dwordx4 v[214:215], off
	v_lshl_add_u64 v[214:215], s[18:19], 0, v[164:165]
	s_add_i32 m0, s24, 0x2000
	s_nop 0
	global_load_lds_dwordx4 v[214:215], off
	v_lshl_add_u64 v[214:215], v[230:231], 0, s[4:5]
	s_mov_b32 m0, s65
	s_nop 0
	global_load_lds_dwordx4 v[214:215], off
	v_lshl_add_u64 v[214:215], v[240:241], 0, s[4:5]
	s_mov_b32 m0, s66
	s_nop 0
	global_load_lds_dwordx4 v[214:215], off
	s_waitcnt vmcnt(8)
	s_waitcnt lgkmcnt(0)
	s_barrier
	s_waitcnt lgkmcnt(0)
	v_mfma_f32_16x16x32_bf16 v[80:83], v[60:63], v[170:173], v[80:83]
	v_mfma_f32_16x16x32_bf16 v[80:83], v[64:67], v[174:177], v[80:83]
	v_mfma_f32_16x16x32_bf16 v[76:79], v[72:75], v[174:177], v[76:79]
	v_mfma_f32_16x16x32_bf16 v[76:79], v[68:71], v[170:173], v[76:79]
	v_mfma_f32_16x16x32_bf16 v[44:47], v[68:71], v[182:185], v[44:47]
	v_mfma_f32_16x16x32_bf16 v[44:47], v[72:75], v[186:189], v[44:47]
	v_mfma_f32_16x16x32_bf16 v[52:55], v[64:67], v[186:189], v[52:55]
	v_mfma_f32_16x16x32_bf16 v[52:55], v[60:63], v[182:185], v[52:55]
	v_mfma_f32_16x16x32_bf16 v[32:35], v[60:63], v[190:193], v[32:35]
	v_mfma_f32_16x16x32_bf16 v[32:35], v[64:67], v[206:209], v[32:35]
	v_mfma_f32_16x16x32_bf16 v[28:31], v[72:75], v[206:209], v[28:31]
	v_mfma_f32_16x16x32_bf16 v[28:31], v[68:71], v[190:193], v[28:31]
	v_mfma_f32_16x16x32_bf16 v[12:15], v[68:71], v[210:213], v[12:15]
	v_mfma_f32_16x16x32_bf16 v[12:15], v[72:75], v[224:227], v[12:15]
	v_mfma_f32_16x16x32_bf16 v[16:19], v[64:67], v[224:227], v[16:19]
	v_mfma_f32_16x16x32_bf16 v[16:19], v[60:63], v[210:213], v[16:19]
	v_mfma_f32_16x16x32_bf16 v[48:51], v[148:151], v[170:173], v[48:51]
	v_mfma_f32_16x16x32_bf16 v[72:75], v[152:155], v[174:177], v[48:51]
	v_mfma_f32_16x16x32_bf16 v[48:51], v[156:159], v[170:173], v[56:59]
	v_mfma_f32_16x16x32_bf16 v[68:71], v[160:163], v[174:177], v[48:51]
	v_mfma_f32_16x16x32_bf16 v[36:39], v[160:163], v[186:189], v[36:39]
	v_mfma_f32_16x16x32_bf16 v[36:39], v[156:159], v[182:185], v[36:39]
	v_mfma_f32_16x16x32_bf16 v[40:43], v[148:151], v[182:185], v[40:43]
	v_mfma_f32_16x16x32_bf16 v[40:43], v[152:155], v[186:189], v[40:43]
	v_mfma_f32_16x16x32_bf16 v[24:27], v[152:155], v[206:209], v[24:27]
	v_mfma_f32_16x16x32_bf16 v[24:27], v[148:151], v[190:193], v[24:27]
	v_mfma_f32_16x16x32_bf16 v[20:23], v[156:159], v[190:193], v[20:23]
	v_mfma_f32_16x16x32_bf16 v[20:23], v[160:163], v[206:209], v[20:23]
	v_mfma_f32_16x16x32_bf16 v[4:7], v[160:163], v[224:227], v[4:7]
	v_mfma_f32_16x16x32_bf16 v[4:7], v[156:159], v[210:213], v[4:7]
	v_mfma_f32_16x16x32_bf16 v[8:11], v[148:151], v[210:213], v[8:11]
	v_mfma_f32_16x16x32_bf16 v[8:11], v[152:155], v[224:227], v[8:11]
	s_barrier
	s_add_i32 s69, s69, 2
	s_add_u32 s55, s55, 0x100
	s_addc_u32 s68, s68, 0
	s_cmp_gt_u32 s69, 61
	s_mov_b64 s[60:61], s[14:15]
	s_cbranch_scc0 .LBB0_1013
	s_and_b64 vcc, exec, s[50:51]
	s_cbranch_vccz .LBB0_1016
	s_barrier

.LBB0_1158:
	s_add_u32 s14, s52, 0xfff00080
	s_addc_u32 s15, s53, -1
	s_add_i32 s59, 0, 0x10000
	s_cmp_eq_u32 s47, 60
	s_cselect_b32 s19, s3, s15
	s_cselect_b32 s18, s24, s14
	v_add_u32_e32 v142, s59, v143
	s_cselect_b32 s15, s25, s45
	s_cselect_b32 s14, s28, s29
	s_add_i32 s62, 0, 0x14000
	ds_read_b128 v[144:147], v142
	ds_read_b128 v[152:155], v142 offset:1024
	ds_read_b128 v[156:159], v142 offset:2048
	ds_read_b128 v[160:163], v142 offset:3072
	v_add_u32_e32 v142, s62, v143
	ds_read_b128 v[164:167], v142
	ds_read_b128 v[168:171], v142 offset:1024
	ds_read_b128 v[172:175], v142 offset:2048
	ds_read_b128 v[176:179], v142 offset:3072
	v_lshl_add_u64 v[192:193], s[52:53], 0, v[138:139]
	s_add_i32 m0, s36, 0xc000
	ds_read_b128 v[180:183], v151
	ds_read_b128 v[184:187], v151 offset:1024
	ds_read_b128 v[188:191], v151 offset:2048
	ds_read_b128 v[206:209], v151 offset:3072
	ds_read_b128 v[210:213], v151 offset:4096
	ds_read_b128 v[224:227], v151 offset:5120
	ds_read_b128 v[228:231], v151 offset:6144
	ds_read_b128 v[240:243], v151 offset:7168
	global_load_lds_dwordx4 v[192:193], off
	v_lshl_add_u64 v[192:193], s[52:53], 0, v[140:141]
	s_add_i32 m0, s36, 0xe000
	s_nop 0
	global_load_lds_dwordx4 v[192:193], off
	s_waitcnt vmcnt(8)
	s_waitcnt lgkmcnt(0)
	s_barrier
	s_waitcnt lgkmcnt(0)
	v_mfma_f32_16x16x32_bf16 v[128:131], v[144:147], v[180:183], v[128:131]
	v_mfma_f32_16x16x32_bf16 v[128:131], v[152:155], v[184:187], v[128:131]
	v_mfma_f32_16x16x32_bf16 v[124:127], v[160:163], v[184:187], v[124:127]
	v_mfma_f32_16x16x32_bf16 v[124:127], v[156:159], v[180:183], v[124:127]
	v_mfma_f32_16x16x32_bf16 v[108:111], v[156:159], v[188:191], v[108:111]
	v_mfma_f32_16x16x32_bf16 v[108:111], v[160:163], v[206:209], v[108:111]
	v_mfma_f32_16x16x32_bf16 v[112:115], v[152:155], v[206:209], v[112:115]
	v_mfma_f32_16x16x32_bf16 v[112:115], v[144:147], v[188:191], v[112:115]
	v_mfma_f32_16x16x32_bf16 v[96:99], v[144:147], v[210:213], v[96:99]
	v_mfma_f32_16x16x32_bf16 v[96:99], v[152:155], v[224:227], v[96:99]
	v_mfma_f32_16x16x32_bf16 v[92:95], v[160:163], v[224:227], v[92:95]
	v_mfma_f32_16x16x32_bf16 v[92:95], v[156:159], v[210:213], v[92:95]
	v_mfma_f32_16x16x32_bf16 v[76:79], v[156:159], v[228:231], v[76:79]
	v_mfma_f32_16x16x32_bf16 v[76:79], v[160:163], v[240:243], v[76:79]
	v_mfma_f32_16x16x32_bf16 v[80:83], v[152:155], v[240:243], v[80:83]
	v_mfma_f32_16x16x32_bf16 v[80:83], v[144:147], v[228:231], v[80:83]
	v_mfma_f32_16x16x32_bf16 v[72:75], v[164:167], v[228:231], v[72:75]
	v_mfma_f32_16x16x32_bf16 v[72:75], v[168:171], v[240:243], v[72:75]
	v_mfma_f32_16x16x32_bf16 v[68:71], v[176:179], v[240:243], v[68:71]
	v_mfma_f32_16x16x32_bf16 v[68:71], v[172:175], v[228:231], v[68:71]
	v_mfma_f32_16x16x32_bf16 v[84:87], v[172:175], v[210:213], v[84:87]
	v_mfma_f32_16x16x32_bf16 v[84:87], v[176:179], v[224:227], v[84:87]
	v_mfma_f32_16x16x32_bf16 v[88:91], v[168:171], v[224:227], v[88:91]
	v_mfma_f32_16x16x32_bf16 v[88:91], v[164:167], v[210:213], v[88:91]
	v_mfma_f32_16x16x32_bf16 v[104:107], v[164:167], v[188:191], v[104:107]
	v_mfma_f32_16x16x32_bf16 v[104:107], v[168:171], v[206:209], v[104:107]
	v_mfma_f32_16x16x32_bf16 v[100:103], v[176:179], v[206:209], v[100:103]
	v_mfma_f32_16x16x32_bf16 v[100:103], v[172:175], v[188:191], v[100:103]
	v_mfma_f32_16x16x32_bf16 v[116:119], v[172:175], v[180:183], v[116:119]
	v_mfma_f32_16x16x32_bf16 v[116:119], v[176:179], v[184:187], v[116:119]
	v_mfma_f32_16x16x32_bf16 v[120:123], v[168:171], v[184:187], v[120:123]
	v_mfma_f32_16x16x32_bf16 v[120:123], v[164:167], v[180:183], v[120:123]
	s_barrier
	s_add_i32 s59, s59, s35
	v_lshl_add_u64 v[192:193], s[14:15], 0, v[2:3]
	s_mov_b32 m0, s59
	ds_read_b128 v[180:183], v151 offset:16384
	ds_read_b128 v[184:187], v151 offset:17408
	ds_read_b128 v[188:191], v151 offset:18432
	ds_read_b128 v[206:209], v151 offset:19456
	ds_read_b128 v[210:213], v151 offset:20480
	ds_read_b128 v[224:227], v151 offset:21504
	ds_read_b128 v[228:231], v151 offset:22528
	ds_read_b128 v[240:243], v151 offset:23552
	global_load_lds_dwordx4 v[192:193], off
	s_add_i32 m0, s59, 0x2000
	s_add_u32 s60, s14, 0x100000
	v_lshl_add_u64 v[214:215], s[14:15], 0, v[132:133]
	s_addc_u32 s61, s15, 0
	s_add_i32 s59, s62, s35
	global_load_lds_dwordx4 v[214:215], off
	v_lshl_add_u64 v[244:245], s[60:61], 0, v[2:3]
	s_mov_b32 m0, s59
	v_lshl_add_u64 v[246:247], s[18:19], 0, v[134:135]
	global_load_lds_dwordx4 v[244:245], off
	v_lshl_add_u64 v[244:245], s[60:61], 0, v[132:133]
	s_add_i32 m0, s59, 0x2000
	s_nop 0
	global_load_lds_dwordx4 v[244:245], off
	v_lshl_add_u64 v[244:245], s[18:19], 0, v[136:137]
	s_mov_b32 m0, s36
	s_nop 0
	global_load_lds_dwordx4 v[244:245], off
	s_mov_b32 m0, s37
	s_nop 0
	global_load_lds_dwordx4 v[246:247], off
	s_waitcnt vmcnt(8)
	s_waitcnt lgkmcnt(0)
	s_barrier
	s_waitcnt lgkmcnt(0)
	v_mfma_f32_16x16x32_bf16 v[64:67], v[144:147], v[180:183], v[64:67]
	v_mfma_f32_16x16x32_bf16 v[64:67], v[152:155], v[184:187], v[64:67]
	v_mfma_f32_16x16x32_bf16 v[60:63], v[160:163], v[184:187], v[60:63]
	v_mfma_f32_16x16x32_bf16 v[60:63], v[156:159], v[180:183], v[60:63]
	v_mfma_f32_16x16x32_bf16 v[44:47], v[156:159], v[188:191], v[44:47]
	v_mfma_f32_16x16x32_bf16 v[44:47], v[160:163], v[206:209], v[44:47]
	v_mfma_f32_16x16x32_bf16 v[48:51], v[152:155], v[206:209], v[48:51]
	v_mfma_f32_16x16x32_bf16 v[48:51], v[144:147], v[188:191], v[48:51]
	v_mfma_f32_16x16x32_bf16 v[32:35], v[144:147], v[210:213], v[32:35]
	v_mfma_f32_16x16x32_bf16 v[32:35], v[152:155], v[224:227], v[32:35]
	v_mfma_f32_16x16x32_bf16 v[28:31], v[160:163], v[224:227], v[28:31]
	v_mfma_f32_16x16x32_bf16 v[28:31], v[156:159], v[210:213], v[28:31]
	v_mfma_f32_16x16x32_bf16 v[12:15], v[156:159], v[228:231], v[12:15]
	v_mfma_f32_16x16x32_bf16 v[12:15], v[160:163], v[240:243], v[12:15]
	v_mfma_f32_16x16x32_bf16 v[16:19], v[152:155], v[240:243], v[16:19]
	v_mfma_f32_16x16x32_bf16 v[16:19], v[144:147], v[228:231], v[16:19]
	v_mfma_f32_16x16x32_bf16 v[8:11], v[164:167], v[228:231], v[8:11]
	v_mfma_f32_16x16x32_bf16 v[8:11], v[168:171], v[240:243], v[8:11]
	v_mfma_f32_16x16x32_bf16 v[4:7], v[176:179], v[240:243], v[4:7]
	v_mfma_f32_16x16x32_bf16 v[4:7], v[172:175], v[228:231], v[4:7]
	v_mfma_f32_16x16x32_bf16 v[20:23], v[172:175], v[210:213], v[20:23]
	v_mfma_f32_16x16x32_bf16 v[20:23], v[176:179], v[224:227], v[20:23]
	v_mfma_f32_16x16x32_bf16 v[24:27], v[168:171], v[224:227], v[24:27]
	v_mfma_f32_16x16x32_bf16 v[24:27], v[164:167], v[210:213], v[24:27]
	v_mfma_f32_16x16x32_bf16 v[40:43], v[164:167], v[188:191], v[40:43]
	v_mfma_f32_16x16x32_bf16 v[40:43], v[168:171], v[206:209], v[40:43]
	v_mfma_f32_16x16x32_bf16 v[36:39], v[176:179], v[206:209], v[36:39]
	v_mfma_f32_16x16x32_bf16 v[36:39], v[172:175], v[188:191], v[36:39]
	v_mfma_f32_16x16x32_bf16 v[52:55], v[172:175], v[180:183], v[52:55]
	v_mfma_f32_16x16x32_bf16 v[52:55], v[176:179], v[184:187], v[52:55]
	v_mfma_f32_16x16x32_bf16 v[56:59], v[168:171], v[184:187], v[56:59]
	v_mfma_f32_16x16x32_bf16 v[56:59], v[164:167], v[180:183], v[56:59]
	s_barrier
	s_add_i32 s59, 0, 0x18000
	v_add_u32_e32 v142, s59, v143
	s_add_i32 s60, 0, 0x1c000
	ds_read_b128 v[144:147], v142
	ds_read_b128 v[152:155], v142 offset:1024
	ds_read_b128 v[156:159], v142 offset:2048
	ds_read_b128 v[160:163], v142 offset:3072
	v_add_u32_e32 v142, s60, v143
	ds_read_b128 v[164:167], v142
	ds_read_b128 v[168:171], v142 offset:1024
	ds_read_b128 v[172:175], v142 offset:2048
	ds_read_b128 v[176:179], v142 offset:3072
	s_add_u32 s18, s18, 0x100000
	s_addc_u32 s19, s19, 0
	s_mov_b32 m0, s54
	v_lshl_add_u64 v[248:249], s[18:19], 0, v[136:137]
	ds_read_b128 v[180:183], v151 offset:32768
	ds_read_b128 v[184:187], v151 offset:33792
	ds_read_b128 v[188:191], v151 offset:34816
	ds_read_b128 v[206:209], v151 offset:35840
	ds_read_b128 v[210:213], v151 offset:36864
	ds_read_b128 v[224:227], v151 offset:37888
	ds_read_b128 v[228:231], v151 offset:38912
	ds_read_b128 v[240:243], v151 offset:39936
	global_load_lds_dwordx4 v[248:249], off
	v_lshl_add_u64 v[248:249], s[18:19], 0, v[134:135]
	s_mov_b32 m0, s55
	s_nop 0
	global_load_lds_dwordx4 v[248:249], off
	s_waitcnt vmcnt(8)
	s_waitcnt lgkmcnt(0)
	s_barrier
	s_waitcnt lgkmcnt(0)
	v_mfma_f32_16x16x32_bf16 v[128:131], v[144:147], v[180:183], v[128:131]
	v_mfma_f32_16x16x32_bf16 v[128:131], v[152:155], v[184:187], v[128:131]
	v_mfma_f32_16x16x32_bf16 v[124:127], v[160:163], v[184:187], v[124:127]
	v_mfma_f32_16x16x32_bf16 v[124:127], v[156:159], v[180:183], v[124:127]
	v_mfma_f32_16x16x32_bf16 v[108:111], v[156:159], v[188:191], v[108:111]
	v_mfma_f32_16x16x32_bf16 v[108:111], v[160:163], v[206:209], v[108:111]
	v_mfma_f32_16x16x32_bf16 v[112:115], v[152:155], v[206:209], v[112:115]
	v_mfma_f32_16x16x32_bf16 v[112:115], v[144:147], v[188:191], v[112:115]
	v_mfma_f32_16x16x32_bf16 v[96:99], v[144:147], v[210:213], v[96:99]
	v_mfma_f32_16x16x32_bf16 v[96:99], v[152:155], v[224:227], v[96:99]
	v_mfma_f32_16x16x32_bf16 v[92:95], v[160:163], v[224:227], v[92:95]
	v_mfma_f32_16x16x32_bf16 v[92:95], v[156:159], v[210:213], v[92:95]
	v_mfma_f32_16x16x32_bf16 v[76:79], v[156:159], v[228:231], v[76:79]
	v_mfma_f32_16x16x32_bf16 v[76:79], v[160:163], v[240:243], v[76:79]
	v_mfma_f32_16x16x32_bf16 v[80:83], v[152:155], v[240:243], v[80:83]
	v_mfma_f32_16x16x32_bf16 v[80:83], v[144:147], v[228:231], v[80:83]
	v_mfma_f32_16x16x32_bf16 v[72:75], v[164:167], v[228:231], v[72:75]
	v_mfma_f32_16x16x32_bf16 v[72:75], v[168:171], v[240:243], v[72:75]
	v_mfma_f32_16x16x32_bf16 v[68:71], v[176:179], v[240:243], v[68:71]
	v_mfma_f32_16x16x32_bf16 v[68:71], v[172:175], v[228:231], v[68:71]
	v_mfma_f32_16x16x32_bf16 v[84:87], v[172:175], v[210:213], v[84:87]
	v_mfma_f32_16x16x32_bf16 v[84:87], v[176:179], v[224:227], v[84:87]
	v_mfma_f32_16x16x32_bf16 v[88:91], v[168:171], v[224:227], v[88:91]
	v_mfma_f32_16x16x32_bf16 v[88:91], v[164:167], v[210:213], v[88:91]
	v_mfma_f32_16x16x32_bf16 v[104:107], v[164:167], v[188:191], v[104:107]
	v_mfma_f32_16x16x32_bf16 v[104:107], v[168:171], v[206:209], v[104:107]
	v_mfma_f32_16x16x32_bf16 v[100:103], v[176:179], v[206:209], v[100:103]
	v_mfma_f32_16x16x32_bf16 v[100:103], v[172:175], v[188:191], v[100:103]
	v_mfma_f32_16x16x32_bf16 v[116:119], v[172:175], v[180:183], v[116:119]
	v_mfma_f32_16x16x32_bf16 v[116:119], v[176:179], v[184:187], v[116:119]
	v_mfma_f32_16x16x32_bf16 v[120:123], v[168:171], v[184:187], v[120:123]
	v_mfma_f32_16x16x32_bf16 v[120:123], v[164:167], v[180:183], v[120:123]
	s_barrier
	s_add_i32 s18, s59, s35
	v_lshl_add_u64 v[192:193], v[192:193], 0, s[4:5]
	s_mov_b32 m0, s18
	ds_read_b128 v[180:183], v151 offset:49152
	ds_read_b128 v[184:187], v151 offset:50176
	ds_read_b128 v[188:191], v151 offset:51200
	ds_read_b128 v[206:209], v151 offset:52224
	ds_read_b128 v[210:213], v151 offset:53248
	ds_read_b128 v[224:227], v151 offset:54272
	ds_read_b128 v[228:231], v151 offset:55296
	ds_read_b128 v[240:243], v151 offset:56320
	global_load_lds_dwordx4 v[192:193], off
	s_add_i32 m0, s18, 0x2000
	s_add_u32 s14, s14, 0x100080
	v_lshl_add_u64 v[192:193], v[214:215], 0, s[4:5]
	s_addc_u32 s15, s15, 0
	s_add_i32 s18, s60, s35
	global_load_lds_dwordx4 v[192:193], off
	v_lshl_add_u64 v[192:193], s[14:15], 0, v[2:3]
	s_mov_b32 m0, s18
	s_nop 0
	global_load_lds_dwordx4 v[192:193], off
	v_lshl_add_u64 v[192:193], s[14:15], 0, v[132:133]
	s_add_i32 m0, s18, 0x2000
	s_nop 0
	global_load_lds_dwordx4 v[192:193], off
	v_lshl_add_u64 v[192:193], v[244:245], 0, s[4:5]
	s_mov_b32 m0, s56
	s_nop 0
	global_load_lds_dwordx4 v[192:193], off
	v_lshl_add_u64 v[192:193], v[246:247], 0, s[4:5]
	s_mov_b32 m0, s57
	s_nop 0
	global_load_lds_dwordx4 v[192:193], off
	s_waitcnt vmcnt(8)
	s_waitcnt lgkmcnt(0)
	s_barrier
	s_waitcnt lgkmcnt(0)
	v_mfma_f32_16x16x32_bf16 v[64:67], v[144:147], v[180:183], v[64:67]
	v_mfma_f32_16x16x32_bf16 v[64:67], v[152:155], v[184:187], v[64:67]
	v_mfma_f32_16x16x32_bf16 v[60:63], v[160:163], v[184:187], v[60:63]
	v_mfma_f32_16x16x32_bf16 v[60:63], v[156:159], v[180:183], v[60:63]
	v_mfma_f32_16x16x32_bf16 v[44:47], v[156:159], v[188:191], v[44:47]
	v_mfma_f32_16x16x32_bf16 v[44:47], v[160:163], v[206:209], v[44:47]
	v_mfma_f32_16x16x32_bf16 v[48:51], v[152:155], v[206:209], v[48:51]
	v_mfma_f32_16x16x32_bf16 v[48:51], v[144:147], v[188:191], v[48:51]
	v_mfma_f32_16x16x32_bf16 v[32:35], v[144:147], v[210:213], v[32:35]
	v_mfma_f32_16x16x32_bf16 v[32:35], v[152:155], v[224:227], v[32:35]
	v_mfma_f32_16x16x32_bf16 v[28:31], v[160:163], v[224:227], v[28:31]
	v_mfma_f32_16x16x32_bf16 v[28:31], v[156:159], v[210:213], v[28:31]
	v_mfma_f32_16x16x32_bf16 v[12:15], v[156:159], v[228:231], v[12:15]
	v_mfma_f32_16x16x32_bf16 v[12:15], v[160:163], v[240:243], v[12:15]
	v_mfma_f32_16x16x32_bf16 v[16:19], v[152:155], v[240:243], v[16:19]
	v_mfma_f32_16x16x32_bf16 v[16:19], v[144:147], v[228:231], v[16:19]
	v_mfma_f32_16x16x32_bf16 v[8:11], v[164:167], v[228:231], v[8:11]
	v_mfma_f32_16x16x32_bf16 v[8:11], v[168:171], v[240:243], v[8:11]
	v_mfma_f32_16x16x32_bf16 v[4:7], v[176:179], v[240:243], v[4:7]
	v_mfma_f32_16x16x32_bf16 v[4:7], v[172:175], v[228:231], v[4:7]
	v_mfma_f32_16x16x32_bf16 v[20:23], v[172:175], v[210:213], v[20:23]
	v_mfma_f32_16x16x32_bf16 v[20:23], v[176:179], v[224:227], v[20:23]
	v_mfma_f32_16x16x32_bf16 v[24:27], v[168:171], v[224:227], v[24:27]
	v_mfma_f32_16x16x32_bf16 v[24:27], v[164:167], v[210:213], v[24:27]
	v_mfma_f32_16x16x32_bf16 v[40:43], v[164:167], v[188:191], v[40:43]
	v_mfma_f32_16x16x32_bf16 v[40:43], v[168:171], v[206:209], v[40:43]
	v_mfma_f32_16x16x32_bf16 v[36:39], v[176:179], v[206:209], v[36:39]
	v_mfma_f32_16x16x32_bf16 v[36:39], v[172:175], v[188:191], v[36:39]
	v_mfma_f32_16x16x32_bf16 v[52:55], v[172:175], v[180:183], v[52:55]
	v_mfma_f32_16x16x32_bf16 v[52:55], v[176:179], v[184:187], v[52:55]
	v_mfma_f32_16x16x32_bf16 v[56:59], v[168:171], v[184:187], v[56:59]
	v_mfma_f32_16x16x32_bf16 v[56:59], v[164:167], v[180:183], v[56:59]
	s_barrier
	s_add_i32 s47, s47, 2
	s_add_u32 s52, s52, 0x100
	s_addc_u32 s53, s53, 0
	s_add_u32 s29, s29, 0x100
	s_addc_u32 s45, s45, 0
	s_cmp_gt_u32 s47, 61
	s_cbranch_scc0 .LBB0_1158
	s_and_b64 vcc, exec, s[42:43]
	s_cbranch_vccz .LBB0_1161
	s_barrier

.LBB0_1237:
	s_add_u32 s14, s52, 0x10000
	s_addc_u32 s15, s53, 0
	s_add_i32 s59, 0, 0x10000
	s_cmpk_eq_i32 s58, 0xa8
	s_cselect_b32 s25, s43, s15
	s_cselect_b32 s24, s42, s14
	s_cselect_b32 s19, s47, s57
	s_cselect_b32 s18, s46, s56
	s_add_i32 s60, 0, 0x14000
	v_add_u32_e32 v80, s59, v197
	v_add_u32_e32 v160, s60, v197
	ds_read_b128 v[60:63], v80
	ds_read_b128 v[68:71], v80 offset:1024
	ds_read_b128 v[76:79], v80 offset:2048
	ds_read_b128 v[80:83], v80 offset:3072
	ds_read_b128 v[148:151], v160
	ds_read_b128 v[152:155], v160 offset:1024
	ds_read_b128 v[156:159], v160 offset:2048
	ds_read_b128 v[160:163], v160 offset:3072
	v_lshl_add_u64 v[184:185], s[52:53], 0, v[188:189]
	s_add_i32 m0, s28, 0xc000
	ds_read_b128 v[164:167], v241
	ds_read_b128 v[168:171], v241 offset:1024
	ds_read_b128 v[172:175], v241 offset:2048
	ds_read_b128 v[176:179], v241 offset:3072
	ds_read_b128 v[180:183], v241 offset:4096
	ds_read_b128 v[206:209], v241 offset:5120
	ds_read_b128 v[210:213], v241 offset:6144
	ds_read_b128 v[224:227], v241 offset:7168
	global_load_lds_dwordx4 v[184:185], off
	v_lshl_add_u64 v[184:185], s[52:53], 0, v[190:191]
	s_add_i32 m0, s28, 0xe000
	s_nop 0
	global_load_lds_dwordx4 v[184:185], off
	s_waitcnt vmcnt(8)
	s_waitcnt lgkmcnt(0)
	s_barrier
	s_waitcnt lgkmcnt(0)
	v_mfma_f32_16x16x32_bf16 v[144:147], v[60:63], v[164:167], v[144:147]
	v_mfma_f32_16x16x32_bf16 v[144:147], v[68:71], v[168:171], v[144:147]
	v_mfma_f32_16x16x32_bf16 v[140:143], v[80:83], v[168:171], v[140:143]
	v_mfma_f32_16x16x32_bf16 v[140:143], v[76:79], v[164:167], v[140:143]
	v_mfma_f32_16x16x32_bf16 v[124:127], v[76:79], v[172:175], v[124:127]
	v_mfma_f32_16x16x32_bf16 v[124:127], v[80:83], v[176:179], v[124:127]
	v_mfma_f32_16x16x32_bf16 v[128:131], v[68:71], v[176:179], v[128:131]
	v_mfma_f32_16x16x32_bf16 v[128:131], v[60:63], v[172:175], v[128:131]
	v_mfma_f32_16x16x32_bf16 v[112:115], v[60:63], v[180:183], v[112:115]
	v_mfma_f32_16x16x32_bf16 v[112:115], v[68:71], v[206:209], v[112:115]
	v_mfma_f32_16x16x32_bf16 v[108:111], v[80:83], v[206:209], v[108:111]
	v_mfma_f32_16x16x32_bf16 v[108:111], v[76:79], v[180:183], v[108:111]
	v_mfma_f32_16x16x32_bf16 v[92:95], v[76:79], v[210:213], v[92:95]
	v_mfma_f32_16x16x32_bf16 v[92:95], v[80:83], v[224:227], v[92:95]
	v_mfma_f32_16x16x32_bf16 v[96:99], v[68:71], v[224:227], v[96:99]
	v_mfma_f32_16x16x32_bf16 v[96:99], v[60:63], v[210:213], v[96:99]
	v_mfma_f32_16x16x32_bf16 v[88:91], v[148:151], v[210:213], v[88:91]
	v_mfma_f32_16x16x32_bf16 v[88:91], v[152:155], v[224:227], v[88:91]
	v_mfma_f32_16x16x32_bf16 v[84:87], v[160:163], v[224:227], v[84:87]
	v_mfma_f32_16x16x32_bf16 v[84:87], v[156:159], v[210:213], v[84:87]
	v_mfma_f32_16x16x32_bf16 v[100:103], v[156:159], v[180:183], v[100:103]
	v_mfma_f32_16x16x32_bf16 v[100:103], v[160:163], v[206:209], v[100:103]
	v_mfma_f32_16x16x32_bf16 v[104:107], v[152:155], v[206:209], v[104:107]
	v_mfma_f32_16x16x32_bf16 v[104:107], v[148:151], v[180:183], v[104:107]
	v_mfma_f32_16x16x32_bf16 v[120:123], v[148:151], v[172:175], v[120:123]
	v_mfma_f32_16x16x32_bf16 v[120:123], v[152:155], v[176:179], v[120:123]
	v_mfma_f32_16x16x32_bf16 v[116:119], v[160:163], v[176:179], v[116:119]
	v_mfma_f32_16x16x32_bf16 v[116:119], v[156:159], v[172:175], v[116:119]
	v_mfma_f32_16x16x32_bf16 v[132:135], v[156:159], v[164:167], v[132:135]
	v_mfma_f32_16x16x32_bf16 v[132:135], v[160:163], v[168:171], v[132:135]
	v_mfma_f32_16x16x32_bf16 v[136:139], v[152:155], v[168:171], v[136:139]
	v_mfma_f32_16x16x32_bf16 v[136:139], v[148:151], v[164:167], v[136:139]
	s_barrier
	s_add_i32 s52, s59, s27
	v_lshl_add_u64 v[184:185], s[18:19], 0, v[2:3]
	s_mov_b32 m0, s52
	ds_read_b128 v[164:167], v241 offset:16384
	ds_read_b128 v[168:171], v241 offset:17408
	ds_read_b128 v[172:175], v241 offset:18432
	ds_read_b128 v[176:179], v241 offset:19456
	ds_read_b128 v[180:183], v241 offset:20480
	ds_read_b128 v[206:209], v241 offset:21504
	ds_read_b128 v[210:213], v241 offset:22528
	ds_read_b128 v[224:227], v241 offset:23552
	global_load_lds_dwordx4 v[184:185], off
	s_add_i32 m0, s52, 0x2000
	s_add_u32 s52, s18, 0x4000
	v_lshl_add_u64 v[192:193], s[18:19], 0, v[186:187]
	s_addc_u32 s53, s19, 0
	s_add_i32 s59, s60, s27
	global_load_lds_dwordx4 v[192:193], off
	v_lshl_add_u64 v[214:215], s[52:53], 0, v[2:3]
	s_mov_b32 m0, s59
	v_lshl_add_u64 v[228:229], s[24:25], 0, v[186:187]
	global_load_lds_dwordx4 v[214:215], off
	v_lshl_add_u64 v[214:215], s[52:53], 0, v[186:187]
	s_add_i32 m0, s59, 0x2000
	s_nop 0
	global_load_lds_dwordx4 v[214:215], off
	v_lshl_add_u64 v[214:215], s[24:25], 0, v[2:3]
	s_mov_b32 m0, s28
	s_nop 0
	global_load_lds_dwordx4 v[214:215], off
	s_mov_b32 m0, s29
	s_nop 0
	global_load_lds_dwordx4 v[228:229], off
	s_waitcnt vmcnt(8)
	s_waitcnt lgkmcnt(0)
	s_barrier
	s_waitcnt lgkmcnt(0)
	v_mfma_f32_16x16x32_bf16 v[72:75], v[60:63], v[164:167], v[72:75]
	v_mfma_f32_16x16x32_bf16 v[72:75], v[68:71], v[168:171], v[72:75]
	v_mfma_f32_16x16x32_bf16 v[64:67], v[80:83], v[168:171], v[64:67]
	v_mfma_f32_16x16x32_bf16 v[64:67], v[76:79], v[164:167], v[64:67]
	v_mfma_f32_16x16x32_bf16 v[44:47], v[76:79], v[172:175], v[44:47]
	v_mfma_f32_16x16x32_bf16 v[44:47], v[80:83], v[176:179], v[44:47]
	v_mfma_f32_16x16x32_bf16 v[48:51], v[68:71], v[176:179], v[48:51]
	v_mfma_f32_16x16x32_bf16 v[48:51], v[60:63], v[172:175], v[48:51]
	v_mfma_f32_16x16x32_bf16 v[32:35], v[60:63], v[180:183], v[32:35]
	v_mfma_f32_16x16x32_bf16 v[32:35], v[68:71], v[206:209], v[32:35]
	v_mfma_f32_16x16x32_bf16 v[28:31], v[80:83], v[206:209], v[28:31]
	v_mfma_f32_16x16x32_bf16 v[28:31], v[76:79], v[180:183], v[28:31]
	v_mfma_f32_16x16x32_bf16 v[12:15], v[76:79], v[210:213], v[12:15]
	v_mfma_f32_16x16x32_bf16 v[12:15], v[80:83], v[224:227], v[12:15]
	v_mfma_f32_16x16x32_bf16 v[16:19], v[68:71], v[224:227], v[16:19]
	v_mfma_f32_16x16x32_bf16 v[16:19], v[60:63], v[210:213], v[16:19]
	v_mfma_f32_16x16x32_bf16 v[8:11], v[148:151], v[210:213], v[8:11]
	v_mfma_f32_16x16x32_bf16 v[8:11], v[152:155], v[224:227], v[8:11]
	v_mfma_f32_16x16x32_bf16 v[4:7], v[160:163], v[224:227], v[4:7]
	v_mfma_f32_16x16x32_bf16 v[4:7], v[156:159], v[210:213], v[4:7]
	v_mfma_f32_16x16x32_bf16 v[20:23], v[156:159], v[180:183], v[20:23]
	v_mfma_f32_16x16x32_bf16 v[20:23], v[160:163], v[206:209], v[20:23]
	v_mfma_f32_16x16x32_bf16 v[24:27], v[152:155], v[206:209], v[24:27]
	v_mfma_f32_16x16x32_bf16 v[24:27], v[148:151], v[180:183], v[24:27]
	v_mfma_f32_16x16x32_bf16 v[40:43], v[148:151], v[172:175], v[40:43]
	v_mfma_f32_16x16x32_bf16 v[40:43], v[152:155], v[176:179], v[40:43]
	v_mfma_f32_16x16x32_bf16 v[36:39], v[160:163], v[176:179], v[36:39]
	v_mfma_f32_16x16x32_bf16 v[36:39], v[156:159], v[172:175], v[36:39]
	v_mfma_f32_16x16x32_bf16 v[52:55], v[156:159], v[164:167], v[52:55]
	v_mfma_f32_16x16x32_bf16 v[52:55], v[160:163], v[168:171], v[52:55]
	v_mfma_f32_16x16x32_bf16 v[56:59], v[152:155], v[168:171], v[56:59]
	v_mfma_f32_16x16x32_bf16 v[56:59], v[148:151], v[164:167], v[56:59]
	s_barrier
	s_add_i32 s52, 0, 0x18000
	s_add_i32 s53, 0, 0x1c000
	v_add_u32_e32 v80, s52, v197
	v_add_u32_e32 v160, s53, v197
	ds_read_b128 v[60:63], v80
	ds_read_b128 v[68:71], v80 offset:1024
	ds_read_b128 v[76:79], v80 offset:2048
	ds_read_b128 v[80:83], v80 offset:3072
	ds_read_b128 v[148:151], v160
	ds_read_b128 v[152:155], v160 offset:1024
	ds_read_b128 v[156:159], v160 offset:2048
	ds_read_b128 v[160:163], v160 offset:3072
	s_add_u32 s24, s24, 0x4000
	s_addc_u32 s25, s25, 0
	s_mov_b32 m0, s30
	v_lshl_add_u64 v[230:231], s[24:25], 0, v[2:3]
	ds_read_b128 v[164:167], v241 offset:32768
	ds_read_b128 v[168:171], v241 offset:33792
	ds_read_b128 v[172:175], v241 offset:34816
	ds_read_b128 v[176:179], v241 offset:35840
	ds_read_b128 v[180:183], v241 offset:36864
	ds_read_b128 v[206:209], v241 offset:37888
	ds_read_b128 v[210:213], v241 offset:38912
	ds_read_b128 v[224:227], v241 offset:39936
	global_load_lds_dwordx4 v[230:231], off
	v_lshl_add_u64 v[230:231], s[24:25], 0, v[186:187]
	s_mov_b32 m0, s31
	s_nop 0
	global_load_lds_dwordx4 v[230:231], off
	s_waitcnt vmcnt(8)
	s_waitcnt lgkmcnt(0)
	s_barrier
	s_waitcnt lgkmcnt(0)
	v_mfma_f32_16x16x32_bf16 v[144:147], v[60:63], v[164:167], v[144:147]
	v_mfma_f32_16x16x32_bf16 v[144:147], v[68:71], v[168:171], v[144:147]
	v_mfma_f32_16x16x32_bf16 v[140:143], v[80:83], v[168:171], v[140:143]
	v_mfma_f32_16x16x32_bf16 v[140:143], v[76:79], v[164:167], v[140:143]
	v_mfma_f32_16x16x32_bf16 v[124:127], v[76:79], v[172:175], v[124:127]
	v_mfma_f32_16x16x32_bf16 v[124:127], v[80:83], v[176:179], v[124:127]
	v_mfma_f32_16x16x32_bf16 v[128:131], v[68:71], v[176:179], v[128:131]
	v_mfma_f32_16x16x32_bf16 v[128:131], v[60:63], v[172:175], v[128:131]
	v_mfma_f32_16x16x32_bf16 v[112:115], v[60:63], v[180:183], v[112:115]
	v_mfma_f32_16x16x32_bf16 v[112:115], v[68:71], v[206:209], v[112:115]
	v_mfma_f32_16x16x32_bf16 v[108:111], v[80:83], v[206:209], v[108:111]
	v_mfma_f32_16x16x32_bf16 v[108:111], v[76:79], v[180:183], v[108:111]
	v_mfma_f32_16x16x32_bf16 v[92:95], v[76:79], v[210:213], v[92:95]
	v_mfma_f32_16x16x32_bf16 v[92:95], v[80:83], v[224:227], v[92:95]
	v_mfma_f32_16x16x32_bf16 v[96:99], v[68:71], v[224:227], v[96:99]
	v_mfma_f32_16x16x32_bf16 v[96:99], v[60:63], v[210:213], v[96:99]
	v_mfma_f32_16x16x32_bf16 v[88:91], v[148:151], v[210:213], v[88:91]
	v_mfma_f32_16x16x32_bf16 v[88:91], v[152:155], v[224:227], v[88:91]
	v_mfma_f32_16x16x32_bf16 v[84:87], v[160:163], v[224:227], v[84:87]
	v_mfma_f32_16x16x32_bf16 v[84:87], v[156:159], v[210:213], v[84:87]
	v_mfma_f32_16x16x32_bf16 v[100:103], v[156:159], v[180:183], v[100:103]
	v_mfma_f32_16x16x32_bf16 v[100:103], v[160:163], v[206:209], v[100:103]
	v_mfma_f32_16x16x32_bf16 v[104:107], v[152:155], v[206:209], v[104:107]
	v_mfma_f32_16x16x32_bf16 v[104:107], v[148:151], v[180:183], v[104:107]
	v_mfma_f32_16x16x32_bf16 v[120:123], v[148:151], v[172:175], v[120:123]
	v_mfma_f32_16x16x32_bf16 v[120:123], v[152:155], v[176:179], v[120:123]
	v_mfma_f32_16x16x32_bf16 v[116:119], v[160:163], v[176:179], v[116:119]
	v_mfma_f32_16x16x32_bf16 v[116:119], v[156:159], v[172:175], v[116:119]
	v_mfma_f32_16x16x32_bf16 v[132:135], v[156:159], v[164:167], v[132:135]
	v_mfma_f32_16x16x32_bf16 v[132:135], v[160:163], v[168:171], v[132:135]
	v_mfma_f32_16x16x32_bf16 v[136:139], v[152:155], v[168:171], v[136:139]
	v_mfma_f32_16x16x32_bf16 v[136:139], v[148:151], v[164:167], v[136:139]
	s_barrier
	s_add_i32 s24, s52, s27
	v_lshl_add_u64 v[184:185], v[184:185], 0, s[96:97]
	s_mov_b32 m0, s24
	ds_read_b128 v[164:167], v241 offset:49152
	ds_read_b128 v[168:171], v241 offset:50176
	ds_read_b128 v[172:175], v241 offset:51200
	ds_read_b128 v[176:179], v241 offset:52224
	ds_read_b128 v[180:183], v241 offset:53248
	ds_read_b128 v[206:209], v241 offset:54272
	ds_read_b128 v[210:213], v241 offset:55296
	ds_read_b128 v[224:227], v241 offset:56320
	global_load_lds_dwordx4 v[184:185], off
	s_add_i32 m0, s24, 0x2000
	s_add_u32 s18, s18, 0xc000
	v_lshl_add_u64 v[184:185], v[192:193], 0, s[96:97]
	s_addc_u32 s19, s19, 0
	s_add_i32 s24, s53, s27
	global_load_lds_dwordx4 v[184:185], off
	v_lshl_add_u64 v[184:185], s[18:19], 0, v[2:3]
	s_mov_b32 m0, s24
	s_nop 0
	global_load_lds_dwordx4 v[184:185], off
	v_lshl_add_u64 v[184:185], s[18:19], 0, v[186:187]
	s_add_i32 m0, s24, 0x2000
	s_nop 0
	global_load_lds_dwordx4 v[184:185], off
	v_lshl_add_u64 v[184:185], v[214:215], 0, s[96:97]
	s_mov_b32 m0, s35
	s_nop 0
	global_load_lds_dwordx4 v[184:185], off
	v_lshl_add_u64 v[184:185], v[228:229], 0, s[96:97]
	s_mov_b32 m0, s36
	s_nop 0
	global_load_lds_dwordx4 v[184:185], off
	s_waitcnt vmcnt(8)
	s_waitcnt lgkmcnt(0)
	s_barrier
	s_waitcnt lgkmcnt(0)
	v_mfma_f32_16x16x32_bf16 v[72:75], v[60:63], v[164:167], v[72:75]
	v_mfma_f32_16x16x32_bf16 v[72:75], v[68:71], v[168:171], v[72:75]
	v_mfma_f32_16x16x32_bf16 v[64:67], v[80:83], v[168:171], v[64:67]
	v_mfma_f32_16x16x32_bf16 v[64:67], v[76:79], v[164:167], v[64:67]
	v_mfma_f32_16x16x32_bf16 v[44:47], v[76:79], v[172:175], v[44:47]
	v_mfma_f32_16x16x32_bf16 v[44:47], v[80:83], v[176:179], v[44:47]
	v_mfma_f32_16x16x32_bf16 v[48:51], v[68:71], v[176:179], v[48:51]
	v_mfma_f32_16x16x32_bf16 v[48:51], v[60:63], v[172:175], v[48:51]
	v_mfma_f32_16x16x32_bf16 v[32:35], v[60:63], v[180:183], v[32:35]
	v_mfma_f32_16x16x32_bf16 v[32:35], v[68:71], v[206:209], v[32:35]
	v_mfma_f32_16x16x32_bf16 v[28:31], v[80:83], v[206:209], v[28:31]
	v_mfma_f32_16x16x32_bf16 v[28:31], v[76:79], v[180:183], v[28:31]
	v_mfma_f32_16x16x32_bf16 v[12:15], v[76:79], v[210:213], v[12:15]
	v_mfma_f32_16x16x32_bf16 v[12:15], v[80:83], v[224:227], v[12:15]
	v_mfma_f32_16x16x32_bf16 v[16:19], v[68:71], v[224:227], v[16:19]
	v_mfma_f32_16x16x32_bf16 v[16:19], v[60:63], v[210:213], v[16:19]
	v_mfma_f32_16x16x32_bf16 v[8:11], v[148:151], v[210:213], v[8:11]
	v_mfma_f32_16x16x32_bf16 v[8:11], v[152:155], v[224:227], v[8:11]
	v_mfma_f32_16x16x32_bf16 v[4:7], v[160:163], v[224:227], v[4:7]
	v_mfma_f32_16x16x32_bf16 v[4:7], v[156:159], v[210:213], v[4:7]
	v_mfma_f32_16x16x32_bf16 v[20:23], v[156:159], v[180:183], v[20:23]
	v_mfma_f32_16x16x32_bf16 v[20:23], v[160:163], v[206:209], v[20:23]
	v_mfma_f32_16x16x32_bf16 v[24:27], v[152:155], v[206:209], v[24:27]
	v_mfma_f32_16x16x32_bf16 v[24:27], v[148:151], v[180:183], v[24:27]
	v_mfma_f32_16x16x32_bf16 v[40:43], v[148:151], v[172:175], v[40:43]
	v_mfma_f32_16x16x32_bf16 v[40:43], v[152:155], v[176:179], v[40:43]
	v_mfma_f32_16x16x32_bf16 v[36:39], v[160:163], v[176:179], v[36:39]
	v_mfma_f32_16x16x32_bf16 v[36:39], v[156:159], v[172:175], v[36:39]
	v_mfma_f32_16x16x32_bf16 v[52:55], v[156:159], v[164:167], v[52:55]
	v_mfma_f32_16x16x32_bf16 v[52:55], v[160:163], v[168:171], v[52:55]
	v_mfma_f32_16x16x32_bf16 v[56:59], v[152:155], v[168:171], v[56:59]
	v_mfma_f32_16x16x32_bf16 v[56:59], v[148:151], v[164:167], v[56:59]
	s_barrier
	s_add_i32 s58, s58, 2
	s_add_u32 s56, s56, 0x10000
	s_addc_u32 s57, s57, 0
	s_cmpk_gt_u32 s58, 0xa9
	s_mov_b64 s[52:53], s[14:15]
	s_cbranch_scc0 .LBB0_1237
	s_and_b64 vcc, exec, s[44:45]
	s_cbranch_vccz .LBB0_1240
	s_barrier
